# layer-1 W13 weight conversion moved into layer-0 FFN2's idle workgroups (96 WGs without a split-K unit), P1(l1) skips W13 tiles
# speedup vs baseline: 1.0071x; 1.0071x over previous
; #define WT_LOAD() do { _Pragma("unroll") for (int i = 0; i < 16; ++i) rg[i] = sp ? sp[(size_t)(k0 + kq + i * 8) * ld] : 0.f; } while (0)
; __device__ __forceinline__ void phase_weights(int wv, const Params& p, int l, LAS unsigned char* lds, int first, int stride) {
;     ...
;     if (ti < 1536) { WT_DECODE(ti); WT_LOAD(); }
;     while (ti < 1536) {
;         bf16_t* cdst = dst + (size_t)n0 * K + k0; const int cK = K;
;         __syncthreads();
; #pragma unroll
;         for (int i = 0; i < 16; ++i) tile[(kq + i * 8) * 65 + nl] = rg[i];
;         ti += stride;
;         if (ti < 1536) { WT_DECODE(ti); WT_LOAD(); }
.LBB0_232:
	s_add_i32 s46, s46, s1
	v_readlane_b32 s101, v255, 22
	s_cmp_lg_u32 s101, 1
	s_cbranch_scc1 .Lws_done
	s_cmpk_lg_u32 s44, 0x100
	s_cbranch_scc1 .Lws_done
.Lws_loop:
	s_cmpk_lt_i32 s46, 0x160
	s_cbranch_scc1 .Lws_done
	s_cmpk_gt_i32 s46, 0x41f
	s_cbranch_scc1 .Lws_done
	s_add_i32 s46, s46, s1
	s_add_i32 s42, s42, s43
	s_branch .Lws_loop
.Lws_done:
	s_cmpk_gt_i32 s46, 0x5ff
	s_cselect_b64 s[36:37], -1, 0
	s_and_b64 vcc, exec, s[36:37]
	s_mov_b32 s49, s56
	s_barrier
	s_waitcnt vmcnt(0)
	ds_write_b32 v28, v2
	ds_write_b32 v28, v3 offset:2080
	ds_write_b32 v28, v4 offset:4160
	ds_write_b32 v28, v5 offset:6240
	ds_write_b32 v28, v6 offset:8320
	ds_write_b32 v28, v7 offset:10400
	ds_write_b32 v28, v8 offset:12480
	ds_write_b32 v28, v9 offset:14560
	ds_write_b32 v28, v10 offset:16640
	ds_write_b32 v28, v11 offset:18720
	ds_write_b32 v28, v12 offset:20800
	ds_write_b32 v28, v13 offset:22880
	ds_write_b32 v28, v14 offset:24960
	ds_write_b32 v28, v15 offset:27040
	ds_write_b32 v28, v16 offset:29120
	ds_write_b32 v28, v17 offset:31200
	s_cbranch_vccnz .LBB0_231
	s_cmpk_gt_i32 s46, 0x49f
	s_mov_b64 s[4:5], -1
	s_cbranch_scc0 .LBB0_235
	s_add_i32 s4, s46, 0xfb60
	s_and_b32 s5, s4, 0xffff
	s_mul_i32 s5, s5, 0xba2f
	s_lshr_b32 s5, s5, 20
	s_lshl_b32 s47, s5, 6
	s_mul_i32 s5, s5, 22
	s_sub_i32 s4, s4, s5
	s_lshl_b32 s4, s4, 7
	s_and_b32 s49, s4, 0xff80
	s_mov_b64 s[4:5], 0

; __device__ __forceinline__ unsigned pk_bf16(float lo, float hi) { unsigned r; asm volatile("v_cvt_pk_bf16_f32 %0, %1, %2" : "=v"(r) : "v"(lo), "v"(hi)); return r; }
; #define WT_LOAD() do { _Pragma("unroll") for (int i = 0; i < 16; ++i) rg[i] = sp ? sp[(size_t)(k0 + kq + i * 8) * ld] : 0.f; } while (0)
; __device__ __forceinline__ void phase_weights(int wv, const Params& p, int l, LAS unsigned char* lds, int first, int stride) {
;     ...
;     if (ti < 1536) { WT_DECODE(ti); WT_LOAD(); }
;     while (ti < 1536) {
;         bf16_t* cdst = dst + (size_t)n0 * K + k0; const int cK = K;
;         __syncthreads();
; #pragma unroll
;         for (int i = 0; i < 16; ++i) tile[(kq + i * 8) * 65 + nl] = rg[i];
;         ti += stride;
;         if (ti < 1536) { WT_DECODE(ti); WT_LOAD(); }
;         __syncthreads();
;         { const int nn = tid >> 3, ks = tid & 7; float v[16];
; #pragma unroll
;             for (int j = 0; j < 16; ++j) v[j] = tile[(ks * 16 + j) * 65 + nn];
;             u32x4 w0, w1; w0.x = pk_bf16(v[0], v[1]); w0.y = pk_bf16(v[2], v[3]); w0.z = pk_bf16(v[4], v[5]); w0.w = pk_bf16(v[6], v[7]);
;             w1.x = pk_bf16(v[8], v[9]); w1.y = pk_bf16(v[10], v[11]); w1.z = pk_bf16(v[12], v[13]); w1.w = pk_bf16(v[14], v[15]);
;             bf16_t* o = cdst + (size_t)nn * cK + ks * 16; *(u32x4*)o = w0; *(u32x4*)(o + 8) = w1; }
.LBB0_1505:
	s_cmpk_lt_u32 s96, 0xa0
	s_cbranch_scc1 .Lew_end
	s_cmpk_lg_u32 s44, 0x100
	s_cbranch_scc1 .Lew_end
	s_load_dwordx2 s[8:9], s[90:91], 0x88
	s_load_dwordx2 s[10:11], s[90:91], 0x90
	s_load_dwordx2 s[12:13], s[90:91], 0xa8
	v_readlane_b32 s24, v255, 7
	v_mbcnt_lo_u32_b32 v2, -1, 0
	v_mbcnt_hi_u32_b32 v2, -1, v2
	v_and_b32_e32 v3, 15, v2
	v_lshrrev_b32_e32 v6, 5, v2
	v_lshlrev_b32_e32 v7, 4, v3
	v_mul_u32_u24_e32 v8, 0x2c000, v6
	v_add_u32_e32 v7, v7, v8
	v_add_u32_e32 v12, 0xb00000, v7
	v_mov_b32_e32 v13, 0
	v_and_b32_e32 v8, 16, v2
	v_cmp_ne_u32_e32 vcc, 0, v8
	s_waitcnt lgkmcnt(0)
	v_mov_b32_e32 v4, s8
	v_mov_b32_e32 v5, s9
	v_mov_b32_e32 v8, s10
	v_mov_b32_e32 v9, s11
	s_nop 1
	v_cndmask_b32_e32 v4, v4, v8, vcc
	v_cndmask_b32_e32 v5, v5, v9, vcc
	v_lshl_add_u64 v[4:5], v[4:5], 0, v[12:13]
	v_and_b32_e32 v8, 1, v3
	v_lshlrev_b32_e32 v10, 7, v8
	v_bfe_u32 v8, v3, 1, 2
	v_lshl_add_u32 v10, v8, 2, v10
	v_lshrrev_b32_e32 v8, 3, v3
	v_lshl_add_u32 v10, v8, 5, v10
	v_bfe_u32 v8, v2, 4, 1
	v_lshl_add_u32 v10, v8, 4, v10
	v_add_u32_e32 v10, 2, v10
	v_lshlrev_b32_e32 v10, 11, v10
	v_lshl_add_u32 v10, v6, 5, v10
	s_add_u32 s12, s12, 0xb34c000
	s_addc_u32 s13, s13, 0
	s_lshr_b32 s24, s24, 6
	s_sub_i32 s3, s96, 0xa0
	s_lshl_b32 s3, s3, 3
	s_add_i32 s3, s3, s24
.Lew_loop:
	s_cmpk_gt_u32 s3, 0x57f
	s_cbranch_scc1 .Lew_end
	s_lshr_b32 s6, s3, 5
	s_and_b32 s7, s3, 31
	s_lshr_b32 s14, s6, 1
	s_and_b32 s15, s6, 1
	s_lshl_b32 s18, s14, 9
	s_lshl_b32 s19, s15, 8
	s_add_i32 s18, s18, s19
	s_mul_i32 s19, s7, 0x58000
	s_add_i32 s20, s18, s19
	s_mov_b32 s21, 0
	v_lshl_add_u64 v[6:7], s[20:21], 0, v[4:5]
	global_load_dwordx4 v[20:23], v[6:7], off
	s_add_u32 s20, s20, 0x2c00
	v_lshl_add_u64 v[8:9], s[20:21], 0, v[4:5]
	global_load_dwordx4 v[24:27], v[8:9], off
	s_add_u32 s20, s20, 0x2c00
	v_lshl_add_u64 v[6:7], s[20:21], 0, v[4:5]
	global_load_dwordx4 v[28:31], v[6:7], off
	s_add_u32 s20, s20, 0x2c00
	v_lshl_add_u64 v[8:9], s[20:21], 0, v[4:5]
	global_load_dwordx4 v[32:35], v[8:9], off
	s_add_u32 s20, s20, 0x2c00
	v_lshl_add_u64 v[6:7], s[20:21], 0, v[4:5]
	global_load_dwordx4 v[36:39], v[6:7], off
	s_add_u32 s20, s20, 0x2c00
	v_lshl_add_u64 v[8:9], s[20:21], 0, v[4:5]
	global_load_dwordx4 v[40:43], v[8:9], off
	s_add_u32 s20, s20, 0x2c00
	v_lshl_add_u64 v[6:7], s[20:21], 0, v[4:5]
	global_load_dwordx4 v[44:47], v[6:7], off
	s_add_u32 s20, s20, 0x2c00
	v_lshl_add_u64 v[8:9], s[20:21], 0, v[4:5]
	global_load_dwordx4 v[48:51], v[8:9], off
	s_add_u32 s20, s20, 0x2c00
	v_lshl_add_u64 v[6:7], s[20:21], 0, v[4:5]
	global_load_dwordx4 v[52:55], v[6:7], off
	s_add_u32 s20, s20, 0x2c00
	v_lshl_add_u64 v[8:9], s[20:21], 0, v[4:5]
	global_load_dwordx4 v[56:59], v[8:9], off
	s_add_u32 s20, s20, 0x2c00
	v_lshl_add_u64 v[6:7], s[20:21], 0, v[4:5]
	global_load_dwordx4 v[60:63], v[6:7], off
	s_add_u32 s20, s20, 0x2c00
	v_lshl_add_u64 v[8:9], s[20:21], 0, v[4:5]
	global_load_dwordx4 v[64:67], v[8:9], off
	s_add_u32 s20, s20, 0x2c00
	v_lshl_add_u64 v[6:7], s[20:21], 0, v[4:5]
	global_load_dwordx4 v[68:71], v[6:7], off
	s_add_u32 s20, s20, 0x2c00
	v_lshl_add_u64 v[8:9], s[20:21], 0, v[4:5]
	global_load_dwordx4 v[72:75], v[8:9], off
	s_add_u32 s20, s20, 0x2c00
	v_lshl_add_u64 v[6:7], s[20:21], 0, v[4:5]
	global_load_dwordx4 v[76:79], v[6:7], off
	s_add_u32 s20, s20, 0x2c00
	v_lshl_add_u64 v[8:9], s[20:21], 0, v[4:5]
	global_load_dwordx4 v[80:83], v[8:9], off
	s_add_u32 s20, s20, 0x2c00
	s_lshl_b32 s18, s14, 19
	s_lshl_b32 s19, s15, 17
	s_add_i32 s18, s18, s19
	s_lshl_b32 s19, s7, 6
	s_add_i32 s18, s18, s19
	s_add_u32 s22, s12, s18
	s_addc_u32 s23, s13, 0
	s_waitcnt vmcnt(0)
	v_cvt_pk_bf16_f32 v84, v20, v24
	v_cvt_pk_bf16_f32 v85, v28, v32
	v_cvt_pk_bf16_f32 v86, v36, v40
	v_cvt_pk_bf16_f32 v87, v44, v48
	v_cvt_pk_bf16_f32 v88, v52, v56
	v_cvt_pk_bf16_f32 v89, v60, v64
	v_cvt_pk_bf16_f32 v90, v68, v72
	v_cvt_pk_bf16_f32 v91, v76, v80
	v_cvt_pk_bf16_f32 v92, v21, v25
	v_cvt_pk_bf16_f32 v93, v29, v33
	v_cvt_pk_bf16_f32 v94, v37, v41
	v_cvt_pk_bf16_f32 v95, v45, v49
	v_cvt_pk_bf16_f32 v96, v53, v57
	v_cvt_pk_bf16_f32 v97, v61, v65
	v_cvt_pk_bf16_f32 v98, v69, v73
	v_cvt_pk_bf16_f32 v99, v77, v81
	v_cvt_pk_bf16_f32 v100, v22, v26
	v_cvt_pk_bf16_f32 v101, v30, v34
	v_cvt_pk_bf16_f32 v102, v38, v42
	v_cvt_pk_bf16_f32 v103, v46, v50
	v_cvt_pk_bf16_f32 v104, v54, v58
	v_cvt_pk_bf16_f32 v105, v62, v66
	v_cvt_pk_bf16_f32 v106, v70, v74
	v_cvt_pk_bf16_f32 v107, v78, v82
	v_cvt_pk_bf16_f32 v108, v23, v27
	v_cvt_pk_bf16_f32 v109, v31, v35
	v_cvt_pk_bf16_f32 v110, v39, v43
	v_cvt_pk_bf16_f32 v111, v47, v51
	v_cvt_pk_bf16_f32 v112, v55, v59
	v_cvt_pk_bf16_f32 v113, v63, v67
	v_cvt_pk_bf16_f32 v114, v71, v75
	v_cvt_pk_bf16_f32 v115, v79, v83
	global_store_dwordx4 v10, v[84:87], s[22:23] offset:-4096
	global_store_dwordx4 v10, v[88:91], s[22:23] offset:-4080
	global_store_dwordx4 v10, v[92:95], s[22:23] offset:-2048
	global_store_dwordx4 v10, v[96:99], s[22:23] offset:-2032
	global_store_dwordx4 v10, v[100:103], s[22:23]
	global_store_dwordx4 v10, v[104:107], s[22:23] offset:16
	global_store_dwordx4 v10, v[108:111], s[22:23] offset:2048
	global_store_dwordx4 v10, v[112:115], s[22:23] offset:2064
	s_addk_i32 s3, 0x300
	s_branch .Lew_loop
